# gu epilogue: removed dead rstd address arithmetic left over from the moved loads
# speedup vs baseline: 1.0004x; 1.0004x over previous
; __device__ __forceinline__ u32x4 pack8(const f32x4 a, const f32x4 b) { u32x4 w; w.x = pk2(a[0], a[1]); w.y = pk2(a[2], a[3]); w.z = pk2(b[0], b[1]); w.w = pk2(b[2], b[3]); return w; }
;     __device__ __forceinline__ void operator()(const Acc& acc, const Unit& u, int wr, int wc, int fr, int fq) const {
;         const int row0 = u.pm * 256 + wr * 64 + fr;
;         float rs[8]; rstd8(ssq, row0, fq, rs);
; #pragma unroll
;         for (int ai = 0; ai < 2; ++ai)
; #pragma unroll
;             for (int m = 0; m < 4; ++m) {
;                 const int row = row0 + ai * 128 + m * 16; const float r1 = rs[ai * 4 + m];
;                 f32x4 o[2];
; #pragma unroll
;                 for (int n = 0; n < 2; ++n) {
;                     const f32x4 gs = acc[ai][0][m][n] * r1, us = acc[ai][1][m][n] * r1, t = gs * -1.4426950408889634f;
;                     f32x4 d; d[0] = __builtin_amdgcn_exp2f(t[0]); d[1] = __builtin_amdgcn_exp2f(t[1]); d[2] = __builtin_amdgcn_exp2f(t[2]); d[3] = __builtin_amdgcn_exp2f(t[3]);
;                     d = d + 1.0f;
;                     f32x4 r; r[0] = __builtin_amdgcn_rcpf(d[0]); r[1] = __builtin_amdgcn_rcpf(d[1]); r[2] = __builtin_amdgcn_rcpf(d[2]); r[3] = __builtin_amdgcn_rcpf(d[3]);
;                     o[n] = (gs * us) * r;
;                 }
;                 *(u32x4*)(hid + (size_t)row * FF + u.pn * 128 + wc * 32 + 8 * fq) = pack8(o[0], o[1]);
.LBB0_342:
	v_lshl_add_u32 v176, s36, 8, v1
	v_ashrrev_i32_e32 v177, 31, v176
	v_or_b32_e32 v172, 16, v176
	v_ashrrev_i32_e32 v173, 31, v172
	v_or_b32_e32 v168, 32, v176
	v_ashrrev_i32_e32 v169, 31, v168
	v_or_b32_e32 v164, 48, v176
	v_ashrrev_i32_e32 v165, 31, v164
	v_add_u32_e32 v158, 0x80, v176
	v_ashrrev_i32_e32 v159, 31, v158
	v_add_u32_e32 v154, 0x90, v176
	v_ashrrev_i32_e32 v155, 31, v154
	v_add_u32_e32 v152, 0xa0, v176
	v_add_u32_e32 v150, 0xb0, v176
	v_ashrrev_i32_e32 v153, 31, v152
	v_ashrrev_i32_e32 v151, 31, v150
	v_lshlrev_b64 v[174:175], 6, v[152:153]
	v_lshlrev_b64 v[204:205], 6, v[150:151]
	v_lshl_add_u64 v[174:175], v[140:141], 0, v[174:175]
	v_lshl_add_u64 v[208:209], v[140:141], 0, v[204:205]
	s_nop 0
	s_andn2_b64 vcc, exec, s[2:3]
	s_mov_b64 s[2:3], -1
	v_mov_b32_e32 v178, v243
	v_pk_mul_f32 v[126:127], v[126:127], v[178:179] op_sel_hi:[1,0]
	v_pk_mul_f32 v[128:129], v[128:129], v[178:179] op_sel_hi:[1,0]
	v_pk_mul_f32 v[120:121], v[120:121], v[178:179] op_sel_hi:[1,0]
	v_pk_mul_f32 v[122:123], v[122:123], v[178:179] op_sel_hi:[1,0]
	v_pk_mul_f32 v[182:183], v[128:129], s[24:25] op_sel_hi:[1,0]
	v_pk_mul_f32 v[184:185], v[126:127], s[24:25] op_sel_hi:[1,0]
	v_pk_mul_f32 v[118:119], v[118:119], v[178:179] op_sel_hi:[1,0]
	v_pk_mul_f32 v[120:121], v[128:129], v[120:121]
	v_pk_mul_f32 v[124:125], v[124:125], v[178:179] op_sel_hi:[1,0]
	v_pk_mul_f32 v[128:129], v[122:123], s[24:25] op_sel_hi:[1,0]
	v_exp_f32_e32 v184, v184
	v_exp_f32_e32 v185, v185
	v_pk_mul_f32 v[118:119], v[126:127], v[118:119]
	v_pk_mul_f32 v[126:127], v[124:125], s[24:25] op_sel_hi:[1,0]
	v_exp_f32_e32 v128, v128
	v_exp_f32_e32 v129, v129
	v_exp_f32_e32 v182, v182
	v_exp_f32_e32 v183, v183
	v_exp_f32_e32 v126, v126
	v_exp_f32_e32 v127, v127
	v_pk_add_f32 v[184:185], v[184:185], 1.0 op_sel_hi:[1,0]
	v_pk_add_f32 v[128:129], v[128:129], 1.0 op_sel_hi:[1,0]
	v_pk_add_f32 v[182:183], v[182:183], 1.0 op_sel_hi:[1,0]
	v_rcp_f32_e32 v184, v184
	v_rcp_f32_e32 v185, v185
	v_pk_add_f32 v[126:127], v[126:127], 1.0 op_sel_hi:[1,0]
	v_rcp_f32_e32 v128, v128
	v_rcp_f32_e32 v129, v129
	v_rcp_f32_e32 v182, v182
	v_rcp_f32_e32 v183, v183
	v_rcp_f32_e32 v126, v126
	v_rcp_f32_e32 v127, v127
	v_pk_mul_f32 v[114:115], v[114:115], v[178:179] op_sel_hi:[1,0]
	v_pk_mul_f32 v[116:117], v[116:117], v[178:179] op_sel_hi:[1,0]
	v_pk_mul_f32 v[114:115], v[122:123], v[114:115]
	v_pk_mul_f32 v[118:119], v[118:119], v[184:185]
	v_pk_mul_f32 v[116:117], v[124:125], v[116:117]
	v_pk_mul_f32 v[114:115], v[114:115], v[128:129]
	v_pk_mul_f32 v[120:121], v[120:121], v[182:183]
	v_pk_mul_f32 v[122:123], v[116:117], v[126:127]
	v_cvt_pk_bf16_f32 v116, v118, v119
	v_cvt_pk_bf16_f32 v117, v120, v121
	v_cvt_pk_bf16_f32 v118, v114, v115
	v_mov_b64_e32 v[114:115], s[6:7]
	v_mad_i64_i32 v[120:121], s[18:19], v176, s60, v[114:115]
	s_lshl_b32 s18, s37, 7
	v_mov_b32_e32 v180, v244
	s_ashr_i32 s19, s18, 31
	s_lshl_b64 s[36:37], s[18:19], 1
	v_lshl_add_u64 v[120:121], v[120:121], 0, s[36:37]
	v_lshl_add_u64 v[120:121], v[120:121], 0, s[0:1]
	v_cvt_pk_bf16_f32 v119, v122, v123
	v_lshl_add_u64 v[120:121], v[120:121], 0, v[138:139]
	v_pk_mul_f32 v[110:111], v[110:111], v[180:181] op_sel_hi:[1,0]
	global_store_dwordx4 v[120:121], v[116:119], off
	v_pk_mul_f32 v[112:113], v[112:113], v[180:181] op_sel_hi:[1,0]
	v_pk_mul_f32 v[104:105], v[104:105], v[180:181] op_sel_hi:[1,0]
	v_pk_mul_f32 v[118:119], v[110:111], s[24:25] op_sel_hi:[1,0]
	v_pk_mul_f32 v[102:103], v[102:103], v[180:181] op_sel_hi:[1,0]
	v_pk_mul_f32 v[106:107], v[106:107], v[180:181] op_sel_hi:[1,0]
	v_pk_mul_f32 v[108:109], v[108:109], v[180:181] op_sel_hi:[1,0]
	v_pk_mul_f32 v[116:117], v[112:113], s[24:25] op_sel_hi:[1,0]
	v_exp_f32_e32 v118, v118
	v_exp_f32_e32 v119, v119
	v_pk_mul_f32 v[102:103], v[110:111], v[102:103]
	v_pk_mul_f32 v[104:105], v[112:113], v[104:105]
	v_pk_mul_f32 v[110:111], v[108:109], s[24:25] op_sel_hi:[1,0]
	v_pk_mul_f32 v[112:113], v[106:107], s[24:25] op_sel_hi:[1,0]
	v_exp_f32_e32 v110, v110
	v_exp_f32_e32 v112, v112
	v_exp_f32_e32 v111, v111
	v_exp_f32_e32 v113, v113
	v_exp_f32_e32 v116, v116
	v_exp_f32_e32 v117, v117
	v_pk_add_f32 v[118:119], v[118:119], 1.0 op_sel_hi:[1,0]
	v_rcp_f32_e32 v118, v118
	v_rcp_f32_e32 v119, v119
	v_pk_add_f32 v[110:111], v[110:111], 1.0 op_sel_hi:[1,0]
	v_pk_add_f32 v[112:113], v[112:113], 1.0 op_sel_hi:[1,0]
	v_rcp_f32_e32 v112, v112
	v_rcp_f32_e32 v110, v110
	v_rcp_f32_e32 v111, v111
	v_rcp_f32_e32 v113, v113
	v_pk_add_f32 v[116:117], v[116:117], 1.0 op_sel_hi:[1,0]
	v_pk_mul_f32 v[100:101], v[100:101], v[180:181] op_sel_hi:[1,0]
	v_pk_mul_f32 v[98:99], v[98:99], v[180:181] op_sel_hi:[1,0]
	v_mov_b32_e32 v174, v245
	v_rcp_f32_e32 v116, v116
	v_rcp_f32_e32 v117, v117
	v_pk_mul_f32 v[102:103], v[102:103], v[118:119]
	v_pk_mul_f32 v[98:99], v[106:107], v[98:99]
	v_pk_mul_f32 v[100:101], v[108:109], v[100:101]
	v_pk_mul_f32 v[104:105], v[104:105], v[116:117]
	v_pk_mul_f32 v[106:107], v[100:101], v[110:111]
	v_pk_mul_f32 v[100:101], v[98:99], v[112:113]
	v_cvt_pk_bf16_f32 v98, v102, v103
	v_mad_i64_i32 v[102:103], s[18:19], v172, s60, v[114:115]
	v_lshl_add_u64 v[102:103], v[102:103], 0, s[36:37]
	v_lshl_add_u64 v[102:103], v[102:103], 0, s[0:1]
	v_cvt_pk_bf16_f32 v99, v104, v105
	v_cvt_pk_bf16_f32 v100, v100, v101
	v_cvt_pk_bf16_f32 v101, v106, v107
	v_lshl_add_u64 v[102:103], v[102:103], 0, v[138:139]
	v_pk_mul_f32 v[94:95], v[94:95], v[174:175] op_sel_hi:[1,0]
	global_store_dwordx4 v[102:103], v[98:101], off
	v_pk_mul_f32 v[96:97], v[96:97], v[174:175] op_sel_hi:[1,0]
	v_pk_mul_f32 v[88:89], v[88:89], v[174:175] op_sel_hi:[1,0]
	v_pk_mul_f32 v[100:101], v[94:95], s[24:25] op_sel_hi:[1,0]
; __device__ __forceinline__ u32x4 pack8(const f32x4 a, const f32x4 b) { u32x4 w; w.x = pk2(a[0], a[1]); w.y = pk2(a[2], a[3]); w.z = pk2(b[0], b[1]); w.w = pk2(b[2], b[3]); return w; }
;     __device__ __forceinline__ void operator()(const Acc& acc, const Unit& u, int wr, int wc, int fr, int fq) const {
;     ...
;                 const int row = row0 + ai * 128 + m * 16; const float r1 = rs[ai * 4 + m];
;                 f32x4 o[2];
; #pragma unroll
;                 for (int n = 0; n < 2; ++n) {
;                     const f32x4 gs = acc[ai][0][m][n] * r1, us = acc[ai][1][m][n] * r1, t = gs * -1.4426950408889634f;
;                     f32x4 d; d[0] = __builtin_amdgcn_exp2f(t[0]); d[1] = __builtin_amdgcn_exp2f(t[1]); d[2] = __builtin_amdgcn_exp2f(t[2]); d[3] = __builtin_amdgcn_exp2f(t[3]);
;                     d = d + 1.0f;
;                     f32x4 r; r[0] = __builtin_amdgcn_rcpf(d[0]); r[1] = __builtin_amdgcn_rcpf(d[1]); r[2] = __builtin_amdgcn_rcpf(d[2]); r[3] = __builtin_amdgcn_rcpf(d[3]);
;                     o[n] = (gs * us) * r;
;                 }
;                 *(u32x4*)(hid + (size_t)row * FF + u.pn * 128 + wc * 32 + 8 * fq) = pack8(o[0], o[1]);
	v_pk_mul_f32 v[86:87], v[86:87], v[174:175] op_sel_hi:[1,0]
	v_pk_mul_f32 v[90:91], v[90:91], v[174:175] op_sel_hi:[1,0]
	v_pk_mul_f32 v[92:93], v[92:93], v[174:175] op_sel_hi:[1,0]
	v_pk_mul_f32 v[98:99], v[96:97], s[24:25] op_sel_hi:[1,0]
	v_exp_f32_e32 v100, v100
	v_exp_f32_e32 v101, v101
	v_pk_mul_f32 v[86:87], v[94:95], v[86:87]
	v_pk_mul_f32 v[88:89], v[96:97], v[88:89]
	v_pk_mul_f32 v[94:95], v[92:93], s[24:25] op_sel_hi:[1,0]
	v_pk_mul_f32 v[96:97], v[90:91], s[24:25] op_sel_hi:[1,0]
	v_exp_f32_e32 v94, v94
	v_exp_f32_e32 v96, v96
	v_exp_f32_e32 v95, v95
	v_exp_f32_e32 v97, v97
	v_exp_f32_e32 v98, v98
	v_exp_f32_e32 v99, v99
	v_pk_add_f32 v[100:101], v[100:101], 1.0 op_sel_hi:[1,0]
	v_rcp_f32_e32 v100, v100
	v_rcp_f32_e32 v101, v101
	v_pk_add_f32 v[94:95], v[94:95], 1.0 op_sel_hi:[1,0]
	v_pk_add_f32 v[96:97], v[96:97], 1.0 op_sel_hi:[1,0]
	v_rcp_f32_e32 v96, v96
	v_rcp_f32_e32 v94, v94
	v_rcp_f32_e32 v95, v95
	v_rcp_f32_e32 v97, v97
	v_pk_add_f32 v[98:99], v[98:99], 1.0 op_sel_hi:[1,0]
	v_pk_mul_f32 v[84:85], v[84:85], v[174:175] op_sel_hi:[1,0]
	v_pk_mul_f32 v[82:83], v[82:83], v[174:175] op_sel_hi:[1,0]
	v_mov_b32_e32 v170, v246
	v_rcp_f32_e32 v98, v98
	v_rcp_f32_e32 v99, v99
	v_pk_mul_f32 v[86:87], v[86:87], v[100:101]
	v_pk_mul_f32 v[82:83], v[90:91], v[82:83]
	v_pk_mul_f32 v[84:85], v[92:93], v[84:85]
	v_pk_mul_f32 v[88:89], v[88:89], v[98:99]
	v_pk_mul_f32 v[90:91], v[84:85], v[94:95]
	v_pk_mul_f32 v[84:85], v[82:83], v[96:97]
	v_cvt_pk_bf16_f32 v82, v86, v87
	v_mad_i64_i32 v[86:87], s[18:19], v168, s60, v[114:115]
	v_lshl_add_u64 v[86:87], v[86:87], 0, s[36:37]
	v_lshl_add_u64 v[86:87], v[86:87], 0, s[0:1]
	v_cvt_pk_bf16_f32 v83, v88, v89
	v_cvt_pk_bf16_f32 v84, v84, v85
	v_cvt_pk_bf16_f32 v85, v90, v91
	v_lshl_add_u64 v[86:87], v[86:87], 0, v[138:139]
	v_pk_mul_f32 v[78:79], v[78:79], v[170:171] op_sel_hi:[1,0]
	global_store_dwordx4 v[86:87], v[82:85], off
	v_pk_mul_f32 v[80:81], v[80:81], v[170:171] op_sel_hi:[1,0]
	v_pk_mul_f32 v[72:73], v[72:73], v[170:171] op_sel_hi:[1,0]
	v_pk_mul_f32 v[84:85], v[78:79], s[24:25] op_sel_hi:[1,0]
	v_pk_mul_f32 v[70:71], v[70:71], v[170:171] op_sel_hi:[1,0]
	v_pk_mul_f32 v[74:75], v[74:75], v[170:171] op_sel_hi:[1,0]
	v_pk_mul_f32 v[76:77], v[76:77], v[170:171] op_sel_hi:[1,0]
	v_pk_mul_f32 v[82:83], v[80:81], s[24:25] op_sel_hi:[1,0]
	v_exp_f32_e32 v84, v84
	v_exp_f32_e32 v85, v85
	v_pk_mul_f32 v[70:71], v[78:79], v[70:71]
	v_pk_mul_f32 v[72:73], v[80:81], v[72:73]
	v_pk_mul_f32 v[78:79], v[76:77], s[24:25] op_sel_hi:[1,0]
	v_pk_mul_f32 v[80:81], v[74:75], s[24:25] op_sel_hi:[1,0]
	v_exp_f32_e32 v78, v78
	v_exp_f32_e32 v80, v80
	v_exp_f32_e32 v79, v79
	v_exp_f32_e32 v81, v81
	v_exp_f32_e32 v82, v82
	v_exp_f32_e32 v83, v83
	v_pk_add_f32 v[84:85], v[84:85], 1.0 op_sel_hi:[1,0]
	v_rcp_f32_e32 v84, v84
	v_rcp_f32_e32 v85, v85
	v_pk_add_f32 v[78:79], v[78:79], 1.0 op_sel_hi:[1,0]
	v_pk_add_f32 v[80:81], v[80:81], 1.0 op_sel_hi:[1,0]
	v_rcp_f32_e32 v80, v80
	v_rcp_f32_e32 v78, v78
	v_rcp_f32_e32 v79, v79
	v_rcp_f32_e32 v81, v81
	v_pk_add_f32 v[82:83], v[82:83], 1.0 op_sel_hi:[1,0]
	v_pk_mul_f32 v[68:69], v[68:69], v[170:171] op_sel_hi:[1,0]
	v_pk_mul_f32 v[66:67], v[66:67], v[170:171] op_sel_hi:[1,0]
	v_mov_b32_e32 v166, v247
	v_rcp_f32_e32 v82, v82
	v_rcp_f32_e32 v83, v83
	v_pk_mul_f32 v[70:71], v[70:71], v[84:85]
	v_pk_mul_f32 v[66:67], v[74:75], v[66:67]
	v_pk_mul_f32 v[68:69], v[76:77], v[68:69]
	v_pk_mul_f32 v[72:73], v[72:73], v[82:83]
	v_pk_mul_f32 v[74:75], v[68:69], v[78:79]
	v_pk_mul_f32 v[68:69], v[66:67], v[80:81]
	v_cvt_pk_bf16_f32 v66, v70, v71
	v_mad_i64_i32 v[70:71], s[18:19], v164, s60, v[114:115]
	v_lshl_add_u64 v[70:71], v[70:71], 0, s[36:37]
	v_lshl_add_u64 v[70:71], v[70:71], 0, s[0:1]
	v_cvt_pk_bf16_f32 v67, v72, v73
	v_cvt_pk_bf16_f32 v68, v68, v69
	v_cvt_pk_bf16_f32 v69, v74, v75
	v_lshl_add_u64 v[70:71], v[70:71], 0, v[138:139]
	v_pk_mul_f32 v[62:63], v[62:63], v[166:167] op_sel_hi:[1,0]
	global_store_dwordx4 v[70:71], v[66:69], off
	v_pk_mul_f32 v[64:65], v[64:65], v[166:167] op_sel_hi:[1,0]
	v_pk_mul_f32 v[56:57], v[56:57], v[166:167] op_sel_hi:[1,0]
	v_pk_mul_f32 v[68:69], v[62:63], s[24:25] op_sel_hi:[1,0]
	v_pk_mul_f32 v[54:55], v[54:55], v[166:167] op_sel_hi:[1,0]
	v_pk_mul_f32 v[58:59], v[58:59], v[166:167] op_sel_hi:[1,0]
	v_pk_mul_f32 v[60:61], v[60:61], v[166:167] op_sel_hi:[1,0]
	v_pk_mul_f32 v[66:67], v[64:65], s[24:25] op_sel_hi:[1,0]
	v_exp_f32_e32 v68, v68
	v_exp_f32_e32 v69, v69
	v_pk_mul_f32 v[54:55], v[62:63], v[54:55]
	v_pk_mul_f32 v[56:57], v[64:65], v[56:57]
	v_pk_mul_f32 v[62:63], v[60:61], s[24:25] op_sel_hi:[1,0]
	v_pk_mul_f32 v[64:65], v[58:59], s[24:25] op_sel_hi:[1,0]
	v_exp_f32_e32 v64, v64
	v_exp_f32_e32 v62, v62
	v_exp_f32_e32 v63, v63
	v_exp_f32_e32 v65, v65
	v_exp_f32_e32 v66, v66
	v_exp_f32_e32 v67, v67
	v_pk_add_f32 v[68:69], v[68:69], 1.0 op_sel_hi:[1,0]
	v_rcp_f32_e32 v68, v68
	v_rcp_f32_e32 v69, v69
	v_pk_add_f32 v[62:63], v[62:63], 1.0 op_sel_hi:[1,0]
	v_pk_add_f32 v[64:65], v[64:65], 1.0 op_sel_hi:[1,0]
	v_rcp_f32_e32 v64, v64
	v_rcp_f32_e32 v62, v62
	v_rcp_f32_e32 v63, v63
	v_rcp_f32_e32 v65, v65
	v_pk_add_f32 v[66:67], v[66:67], 1.0 op_sel_hi:[1,0]
	v_pk_mul_f32 v[52:53], v[52:53], v[166:167] op_sel_hi:[1,0]
	v_pk_mul_f32 v[50:51], v[50:51], v[166:167] op_sel_hi:[1,0]
	v_mov_b32_e32 v162, v248
	v_rcp_f32_e32 v66, v66
	v_rcp_f32_e32 v67, v67
	v_pk_mul_f32 v[54:55], v[54:55], v[68:69]
	v_pk_mul_f32 v[50:51], v[58:59], v[50:51]
	v_pk_mul_f32 v[52:53], v[60:61], v[52:53]
	v_pk_mul_f32 v[56:57], v[56:57], v[66:67]
	v_pk_mul_f32 v[58:59], v[52:53], v[62:63]
	v_pk_mul_f32 v[52:53], v[50:51], v[64:65]
	v_cvt_pk_bf16_f32 v50, v54, v55
; __device__ __forceinline__ u32x4 pack8(const f32x4 a, const f32x4 b) { u32x4 w; w.x = pk2(a[0], a[1]); w.y = pk2(a[2], a[3]); w.z = pk2(b[0], b[1]); w.w = pk2(b[2], b[3]); return w; }
;     __device__ __forceinline__ void operator()(const Acc& acc, const Unit& u, int wr, int wc, int fr, int fq) const {
;     ...
;                 const int row = row0 + ai * 128 + m * 16; const float r1 = rs[ai * 4 + m];
;                 f32x4 o[2];
; #pragma unroll
;                 for (int n = 0; n < 2; ++n) {
;                     const f32x4 gs = acc[ai][0][m][n] * r1, us = acc[ai][1][m][n] * r1, t = gs * -1.4426950408889634f;
;                     f32x4 d; d[0] = __builtin_amdgcn_exp2f(t[0]); d[1] = __builtin_amdgcn_exp2f(t[1]); d[2] = __builtin_amdgcn_exp2f(t[2]); d[3] = __builtin_amdgcn_exp2f(t[3]);
;                     d = d + 1.0f;
;                     f32x4 r; r[0] = __builtin_amdgcn_rcpf(d[0]); r[1] = __builtin_amdgcn_rcpf(d[1]); r[2] = __builtin_amdgcn_rcpf(d[2]); r[3] = __builtin_amdgcn_rcpf(d[3]);
;                     o[n] = (gs * us) * r;
;                 }
;                 *(u32x4*)(hid + (size_t)row * FF + u.pn * 128 + wc * 32 + 8 * fq) = pack8(o[0], o[1]);
	v_mad_i64_i32 v[54:55], s[18:19], v158, s60, v[114:115]
	v_lshl_add_u64 v[54:55], v[54:55], 0, s[36:37]
	v_lshl_add_u64 v[54:55], v[54:55], 0, s[0:1]
	v_cvt_pk_bf16_f32 v51, v56, v57
	v_cvt_pk_bf16_f32 v52, v52, v53
	v_cvt_pk_bf16_f32 v53, v58, v59
	v_lshl_add_u64 v[54:55], v[54:55], 0, v[138:139]
	v_pk_mul_f32 v[46:47], v[46:47], v[162:163] op_sel_hi:[1,0]
	global_store_dwordx4 v[54:55], v[50:53], off
	v_pk_mul_f32 v[48:49], v[48:49], v[162:163] op_sel_hi:[1,0]
	v_pk_mul_f32 v[40:41], v[40:41], v[162:163] op_sel_hi:[1,0]
	v_pk_mul_f32 v[52:53], v[46:47], s[24:25] op_sel_hi:[1,0]
	v_pk_mul_f32 v[38:39], v[38:39], v[162:163] op_sel_hi:[1,0]
	v_pk_mul_f32 v[42:43], v[42:43], v[162:163] op_sel_hi:[1,0]
	v_pk_mul_f32 v[44:45], v[44:45], v[162:163] op_sel_hi:[1,0]
	v_pk_mul_f32 v[50:51], v[48:49], s[24:25] op_sel_hi:[1,0]
	v_exp_f32_e32 v52, v52
	v_exp_f32_e32 v53, v53
	v_pk_mul_f32 v[38:39], v[46:47], v[38:39]
	v_pk_mul_f32 v[40:41], v[48:49], v[40:41]
	v_pk_mul_f32 v[46:47], v[44:45], s[24:25] op_sel_hi:[1,0]
	v_pk_mul_f32 v[48:49], v[42:43], s[24:25] op_sel_hi:[1,0]
	v_exp_f32_e32 v48, v48
	v_exp_f32_e32 v46, v46
	v_exp_f32_e32 v47, v47
	v_exp_f32_e32 v49, v49
	v_exp_f32_e32 v50, v50
	v_exp_f32_e32 v51, v51
	v_pk_add_f32 v[52:53], v[52:53], 1.0 op_sel_hi:[1,0]
	v_rcp_f32_e32 v52, v52
	v_rcp_f32_e32 v53, v53
	v_pk_add_f32 v[46:47], v[46:47], 1.0 op_sel_hi:[1,0]
	v_pk_add_f32 v[48:49], v[48:49], 1.0 op_sel_hi:[1,0]
	v_rcp_f32_e32 v48, v48
	v_rcp_f32_e32 v46, v46
	v_rcp_f32_e32 v47, v47
	v_rcp_f32_e32 v49, v49
	v_pk_add_f32 v[50:51], v[50:51], 1.0 op_sel_hi:[1,0]
	v_pk_mul_f32 v[36:37], v[36:37], v[162:163] op_sel_hi:[1,0]
	v_pk_mul_f32 v[34:35], v[34:35], v[162:163] op_sel_hi:[1,0]
	v_mov_b32_e32 v160, v249
	v_rcp_f32_e32 v50, v50
	v_rcp_f32_e32 v51, v51
	v_pk_mul_f32 v[38:39], v[38:39], v[52:53]
	v_pk_mul_f32 v[34:35], v[42:43], v[34:35]
	v_pk_mul_f32 v[36:37], v[44:45], v[36:37]
	v_pk_mul_f32 v[40:41], v[40:41], v[50:51]
	v_pk_mul_f32 v[42:43], v[36:37], v[46:47]
	v_pk_mul_f32 v[36:37], v[34:35], v[48:49]
	v_cvt_pk_bf16_f32 v34, v38, v39
	v_mad_i64_i32 v[38:39], s[18:19], v154, s60, v[114:115]
	v_lshl_add_u64 v[38:39], v[38:39], 0, s[36:37]
	v_lshl_add_u64 v[38:39], v[38:39], 0, s[0:1]
	v_cvt_pk_bf16_f32 v35, v40, v41
	v_cvt_pk_bf16_f32 v36, v36, v37
	v_cvt_pk_bf16_f32 v37, v42, v43
	v_lshl_add_u64 v[38:39], v[38:39], 0, v[138:139]
	v_pk_mul_f32 v[30:31], v[30:31], v[160:161] op_sel_hi:[1,0]
	global_store_dwordx4 v[38:39], v[34:37], off
	v_pk_mul_f32 v[32:33], v[32:33], v[160:161] op_sel_hi:[1,0]
	v_pk_mul_f32 v[24:25], v[24:25], v[160:161] op_sel_hi:[1,0]
	v_pk_mul_f32 v[36:37], v[30:31], s[24:25] op_sel_hi:[1,0]
	v_pk_mul_f32 v[22:23], v[22:23], v[160:161] op_sel_hi:[1,0]
	v_pk_mul_f32 v[26:27], v[26:27], v[160:161] op_sel_hi:[1,0]
	v_pk_mul_f32 v[28:29], v[28:29], v[160:161] op_sel_hi:[1,0]
	v_pk_mul_f32 v[34:35], v[32:33], s[24:25] op_sel_hi:[1,0]
	v_exp_f32_e32 v36, v36
	v_exp_f32_e32 v37, v37
	v_pk_mul_f32 v[22:23], v[30:31], v[22:23]
	v_pk_mul_f32 v[24:25], v[32:33], v[24:25]
	v_pk_mul_f32 v[30:31], v[28:29], s[24:25] op_sel_hi:[1,0]
	v_pk_mul_f32 v[32:33], v[26:27], s[24:25] op_sel_hi:[1,0]
	v_exp_f32_e32 v32, v32
	v_exp_f32_e32 v30, v30
	v_exp_f32_e32 v31, v31
	v_exp_f32_e32 v33, v33
	v_exp_f32_e32 v34, v34
	v_exp_f32_e32 v35, v35
	v_pk_add_f32 v[36:37], v[36:37], 1.0 op_sel_hi:[1,0]
	v_rcp_f32_e32 v36, v36
	v_rcp_f32_e32 v37, v37
	v_pk_add_f32 v[30:31], v[30:31], 1.0 op_sel_hi:[1,0]
	v_pk_add_f32 v[32:33], v[32:33], 1.0 op_sel_hi:[1,0]
	v_rcp_f32_e32 v32, v32
	v_rcp_f32_e32 v30, v30
	v_rcp_f32_e32 v31, v31
	v_rcp_f32_e32 v33, v33
	v_pk_add_f32 v[34:35], v[34:35], 1.0 op_sel_hi:[1,0]
	v_pk_mul_f32 v[20:21], v[20:21], v[160:161] op_sel_hi:[1,0]
	v_pk_mul_f32 v[18:19], v[18:19], v[160:161] op_sel_hi:[1,0]
	v_mov_b32_e32 v156, v250
	v_rcp_f32_e32 v34, v34
	v_rcp_f32_e32 v35, v35
	v_pk_mul_f32 v[22:23], v[22:23], v[36:37]
	v_pk_mul_f32 v[18:19], v[26:27], v[18:19]
	v_pk_mul_f32 v[20:21], v[28:29], v[20:21]
	v_pk_mul_f32 v[24:25], v[24:25], v[34:35]
	v_pk_mul_f32 v[26:27], v[20:21], v[30:31]
	v_pk_mul_f32 v[20:21], v[18:19], v[32:33]
	v_cvt_pk_bf16_f32 v18, v22, v23
	v_mad_i64_i32 v[22:23], s[18:19], v152, s60, v[114:115]
	v_lshl_add_u64 v[22:23], v[22:23], 0, s[36:37]
	v_lshl_add_u64 v[22:23], v[22:23], 0, s[0:1]
	v_cvt_pk_bf16_f32 v19, v24, v25
	v_cvt_pk_bf16_f32 v20, v20, v21
	v_cvt_pk_bf16_f32 v21, v26, v27
	v_lshl_add_u64 v[22:23], v[22:23], 0, v[138:139]
	v_pk_mul_f32 v[14:15], v[14:15], v[156:157] op_sel_hi:[1,0]
	global_store_dwordx4 v[22:23], v[18:21], off
	v_pk_mul_f32 v[16:17], v[16:17], v[156:157] op_sel_hi:[1,0]
	v_pk_mul_f32 v[8:9], v[8:9], v[156:157] op_sel_hi:[1,0]
	v_pk_mul_f32 v[20:21], v[14:15], s[24:25] op_sel_hi:[1,0]
	v_pk_mul_f32 v[6:7], v[6:7], v[156:157] op_sel_hi:[1,0]
	v_pk_mul_f32 v[10:11], v[10:11], v[156:157] op_sel_hi:[1,0]
	v_pk_mul_f32 v[12:13], v[12:13], v[156:157] op_sel_hi:[1,0]
	v_pk_mul_f32 v[18:19], v[16:17], s[24:25] op_sel_hi:[1,0]
	v_exp_f32_e32 v20, v20
	v_exp_f32_e32 v21, v21
	v_pk_mul_f32 v[6:7], v[14:15], v[6:7]
	v_pk_mul_f32 v[8:9], v[16:17], v[8:9]
	v_pk_mul_f32 v[14:15], v[12:13], s[24:25] op_sel_hi:[1,0]
	v_pk_mul_f32 v[16:17], v[10:11], s[24:25] op_sel_hi:[1,0]
	v_exp_f32_e32 v14, v14
	v_exp_f32_e32 v16, v16
	v_exp_f32_e32 v15, v15
	v_exp_f32_e32 v17, v17
	v_pk_add_f32 v[20:21], v[20:21], 1.0 op_sel_hi:[1,0]
	v_exp_f32_e32 v18, v18
	v_exp_f32_e32 v19, v19
	v_rcp_f32_e32 v20, v20
	v_rcp_f32_e32 v21, v21
	v_pk_add_f32 v[14:15], v[14:15], 1.0 op_sel_hi:[1,0]
	v_pk_add_f32 v[16:17], v[16:17], 1.0 op_sel_hi:[1,0]
	v_rcp_f32_e32 v14, v14
	v_rcp_f32_e32 v16, v16
	v_rcp_f32_e32 v15, v15
	v_rcp_f32_e32 v17, v17
	v_pk_mul_f32 v[4:5], v[4:5], v[156:157] op_sel_hi:[1,0]
	v_pk_mul_f32 v[2:3], v[2:3], v[156:157] op_sel_hi:[1,0]
	v_pk_add_f32 v[18:19], v[18:19], 1.0 op_sel_hi:[1,0]
	v_pk_mul_f32 v[6:7], v[6:7], v[20:21]
	v_pk_mul_f32 v[2:3], v[10:11], v[2:3]
	v_pk_mul_f32 v[4:5], v[12:13], v[4:5]
	v_rcp_f32_e32 v18, v18
	v_rcp_f32_e32 v19, v19
	v_pk_mul_f32 v[10:11], v[4:5], v[14:15]
	v_pk_mul_f32 v[4:5], v[2:3], v[16:17]
	v_cvt_pk_bf16_f32 v2, v6, v7
	v_mad_i64_i32 v[6:7], s[18:19], v150, s60, v[114:115]
	v_lshl_add_u64 v[6:7], v[6:7], 0, s[36:37]
	v_lshl_add_u64 v[6:7], v[6:7], 0, s[0:1]
	v_lshl_add_u64 v[6:7], v[6:7], 0, v[138:139]
	v_pk_mul_f32 v[8:9], v[8:9], v[18:19]
	s_nop 0
	v_cvt_pk_bf16_f32 v3, v8, v9
	v_cvt_pk_bf16_f32 v4, v4, v5
	v_cvt_pk_bf16_f32 v5, v10, v11
	global_store_dwordx4 v[6:7], v[2:5], off
	s_cbranch_vccnz .LBB0_331
	s_andn2_b64 vcc, exec, s[4:5]
	s_cbranch_vccnz .LBB0_330
	s_barrier
	s_branch .LBB0_330
